# split scan/attention, attention throttle as two s_sleep 64 per tile (tile start and before PV)
# baseline (speedup 1.0000x reference)
; #define LAS __attribute__((address_space(3)))
; __device__ __forceinline__ void phase_attn(const Params& p, int l, LAS unsigned char* ldsb) {
;     ...
;         for (int rt = 0; rt < 4; ++rt) {
;             const int q0 = (wid & 1) * 64 + rt * 16, kstart = q0 < 96 ? q0 : 96;
;             bf16x8 qa0, qa1; { const bf16_t* qp = QKV + (size_t)(tokc + q0 + fr) * 768 + hq * 64 + fq * 8; qa0 = *(const bf16x8*)qp; qa1 = *(const bf16x8*)(qp + 32); }
;             f32x4 S[10];
; #pragma unroll
;             for (int kt = 0; kt < 10; ++kt) {
;                 LAS const bf16_t* kp = Ks + (kstart + kt * 16 + fr) * 72 + fq * 8;
;                 const bf16x8 k0 = *(LAS const bf16x8*)kp, k1 = *(LAS const bf16x8*)(kp + 32);
;                 f32x4 z = (f32x4){0.f, 0.f, 0.f, 0.f};
;                 z = __builtin_amdgcn_mfma_f32_16x16x32_bf16(qa0, k0, z, 0, 0, 0);
;                 z = __builtin_amdgcn_mfma_f32_16x16x32_bf16(qa1, k1, z, 0, 0, 0);
;                 S[kt] = z;
;             }
;             float mx[4] = {-INFINITY, -INFINITY, -INFINITY, -INFINITY};
; #pragma unroll
;             for (int kt = 0; kt < 10; ++kt)
; #pragma unroll
;                 for (int j = 0; j < 4; ++j) {
;                     const int key = kstart + kt * 16 + fr, dist = q0 + 4 * fq + j + 128 - key;
;                     const bool ok = (dist >= 0) && (dist < 128) && (n > 0 || key >= 128);
;                     const float s = ok ? (S[kt][j] * 0.125f + biasL[hl * 128 + (dist & 127)]) : -INFINITY;
;                     S[kt][j] = s; mx[j] = fmaxf(mx[j], s);
;                 }
.Lat_rt:
	s_sleep 64
	s_and_b32 s51, s48, 3
	s_lshl_b32 s51, s51, 4
	s_lshl_b32 s49, s46, 6
	s_add_u32 s49, s49, s51
	s_min_u32 s50, s49, 96
	s_lshr_b32 s51, s48, 2
	s_lshl_b32 s81, s51, 13
	s_add_u32 s81, s81, s32
	s_add_u32 s81, s81, s49
	s_lshl_b32 s81, s81, 10
	s_lshl_b32 s84, s47, 7
	s_add_u32 s81, s81, s84
	s_add_u32 s81, s81, 0x7000000
	s_add_u32 s42, s74, s81
	s_addc_u32 s43, s75, 0
	s_lshl_b32 s51, s51, 16
	s_lshl_b32 s81, s50, 7
	s_add_u32 s51, s51, s81
	v_add_u32_e32 v15, s51, v13
	v_add_u32_e32 v16, s51, v14
	v_add_u32_e32 v23, s51, v19
	v_add_u32_e32 v24, s51, v20
	v_add_u32_e32 v25, s51, v21
	v_add_u32_e32 v26, s51, v22
	s_sub_u32 s81, s49, s50
	s_sub_u32 s81, 32, s81
	s_lshl_b32 s81, s81, 2
	v_add_u32_e32 v18, s81, v17
	s_sub_u32 s84, 128, s50
	s_lshr_b32 s84, s84, 4
	s_cmp_eq_u32 s13, 0
	s_cselect_b32 s84, s84, 0
	ds_read_b128 v[104:107], v18 offset:0
	ds_read_b128 v[108:111], v18 offset:64
	ds_read_b128 v[112:115], v18 offset:128
	ds_read_b128 v[116:119], v18 offset:192
	ds_read_b128 v[120:123], v18 offset:256
	ds_read_b128 v[124:127], v18 offset:320
	ds_read_b128 v[128:131], v18 offset:384
	ds_read_b128 v[132:135], v18 offset:448
	ds_read_b128 v[136:139], v18 offset:512
	ds_read_b128 v[140:143], v18 offset:576
	ds_read_b128 v[48:51], v15 offset:0
	ds_read_b128 v[52:55], v16 offset:0
	ds_read_b128 v[56:59], v15 offset:2048
	ds_read_b128 v[60:63], v16 offset:2048
	s_waitcnt lgkmcnt(2)
	v_mfma_f32_16x16x32_bf16 v[64:67], v[48:51], v[40:43], 0
	v_mfma_f32_16x16x32_bf16 v[64:67], v[52:55], v[44:47], v[64:67]
	ds_read_b128 v[48:51], v15 offset:4096
	ds_read_b128 v[52:55], v16 offset:4096
	s_waitcnt lgkmcnt(2)
	v_mfma_f32_16x16x32_bf16 v[68:71], v[56:59], v[40:43], 0
	v_mfma_f32_16x16x32_bf16 v[68:71], v[60:63], v[44:47], v[68:71]
	ds_read_b128 v[56:59], v15 offset:6144
	ds_read_b128 v[60:63], v16 offset:6144
	s_waitcnt lgkmcnt(2)
	v_mfma_f32_16x16x32_bf16 v[72:75], v[48:51], v[40:43], 0
	v_mfma_f32_16x16x32_bf16 v[72:75], v[52:55], v[44:47], v[72:75]
	ds_read_b128 v[48:51], v15 offset:8192
	ds_read_b128 v[52:55], v16 offset:8192
	s_waitcnt lgkmcnt(2)
	v_mfma_f32_16x16x32_bf16 v[76:79], v[56:59], v[40:43], 0
	v_mfma_f32_16x16x32_bf16 v[76:79], v[60:63], v[44:47], v[76:79]
	ds_read_b128 v[56:59], v15 offset:10240
	ds_read_b128 v[60:63], v16 offset:10240
	s_waitcnt lgkmcnt(2)
	v_mfma_f32_16x16x32_bf16 v[80:83], v[48:51], v[40:43], 0
	v_mfma_f32_16x16x32_bf16 v[80:83], v[52:55], v[44:47], v[80:83]
	ds_read_b128 v[48:51], v15 offset:12288
	ds_read_b128 v[52:55], v16 offset:12288
	s_waitcnt lgkmcnt(2)
	v_mfma_f32_16x16x32_bf16 v[84:87], v[56:59], v[40:43], 0
	v_mfma_f32_16x16x32_bf16 v[84:87], v[60:63], v[44:47], v[84:87]
	ds_read_b128 v[56:59], v15 offset:14336
	ds_read_b128 v[60:63], v16 offset:14336
	s_waitcnt lgkmcnt(2)
	v_mfma_f32_16x16x32_bf16 v[88:91], v[48:51], v[40:43], 0
	v_mfma_f32_16x16x32_bf16 v[88:91], v[52:55], v[44:47], v[88:91]
	ds_read_b128 v[48:51], v15 offset:16384
	ds_read_b128 v[52:55], v16 offset:16384
	s_waitcnt lgkmcnt(2)
	v_mfma_f32_16x16x32_bf16 v[92:95], v[56:59], v[40:43], 0
	v_mfma_f32_16x16x32_bf16 v[92:95], v[60:63], v[44:47], v[92:95]
	ds_read_b128 v[56:59], v15 offset:18432
	ds_read_b128 v[60:63], v16 offset:18432
	s_waitcnt lgkmcnt(2)
	v_mfma_f32_16x16x32_bf16 v[96:99], v[48:51], v[40:43], 0
	v_mfma_f32_16x16x32_bf16 v[96:99], v[52:55], v[44:47], v[96:99]
	s_waitcnt lgkmcnt(0)
	v_mfma_f32_16x16x32_bf16 v[100:103], v[56:59], v[40:43], 0
	v_mfma_f32_16x16x32_bf16 v[100:103], v[60:63], v[44:47], v[100:103]
	s_add_u32 s51, s48, 1
	s_min_u32 s51, s51, 7
	s_lshr_b32 s81, s51, 2
	s_lshl_b32 s81, s81, 13
	s_and_b32 s51, s51, 3
	s_lshl_b32 s51, s51, 4
	s_add_u32 s81, s81, s51
	s_lshl_b32 s51, s46, 6
	s_add_u32 s81, s81, s51
	s_add_u32 s81, s81, s32
	s_mul_i32 s81, s81, 1536
	s_lshl_b32 s51, s47, 7
	s_add_u32 s81, s81, s51
	s_add_u32 s40, s74, s81
	s_addc_u32 s41, s75, 0
	global_load_dwordx4 v[40:43], v27, s[40:41]
	global_load_dwordx4 v[44:47], v27, s[40:41] offset:64
	v_fma_f32 v64, v64, s82, v104
	v_fma_f32 v65, v65, s82, v105
	v_fma_f32 v66, v66, s82, v106
	v_fma_f32 v67, v67, s82, v107
	v_fma_f32 v68, v68, s82, v108
	v_fma_f32 v69, v69, s82, v109
	v_fma_f32 v70, v70, s82, v110
	v_fma_f32 v71, v71, s82, v111
	v_fma_f32 v72, v72, s82, v112
	v_fma_f32 v73, v73, s82, v113
	v_fma_f32 v74, v74, s82, v114
	v_fma_f32 v75, v75, s82, v115
	v_fma_f32 v76, v76, s82, v116
	v_fma_f32 v77, v77, s82, v117
	v_fma_f32 v78, v78, s82, v118
	v_fma_f32 v79, v79, s82, v119
	v_fma_f32 v80, v80, s82, v120
	v_fma_f32 v81, v81, s82, v121
	v_fma_f32 v82, v82, s82, v122
	v_fma_f32 v83, v83, s82, v123
	v_fma_f32 v84, v84, s82, v124
	v_fma_f32 v85, v85, s82, v125
	v_fma_f32 v86, v86, s82, v126
	v_fma_f32 v87, v87, s82, v127
	v_fma_f32 v88, v88, s82, v128
	v_fma_f32 v89, v89, s82, v129
	v_fma_f32 v90, v90, s82, v130
	v_fma_f32 v91, v91, s82, v131
	v_fma_f32 v92, v92, s82, v132
	v_fma_f32 v93, v93, s82, v133
	v_fma_f32 v94, v94, s82, v134
	v_fma_f32 v95, v95, s82, v135
	v_fma_f32 v96, v96, s82, v136
	v_fma_f32 v97, v97, s82, v137
	v_fma_f32 v98, v98, s82, v138
	v_fma_f32 v99, v99, s82, v139
	v_fma_f32 v100, v100, s82, v140
	v_fma_f32 v101, v101, s82, v141
	v_fma_f32 v102, v102, s82, v142
	v_fma_f32 v103, v103, s82, v143
	s_cmp_eq_u32 s84, 0
	s_nop 0
	s_cbranch_scc1 .Lat_nomask
	s_cmp_gt_u32 s84, 0
	s_cselect_b32 s86, 0xff800000, 0
	v_add_f32_e32 v64, s86, v64
	v_add_f32_e32 v65, s86, v65
	v_add_f32_e32 v66, s86, v66
	v_add_f32_e32 v67, s86, v67
	s_cmp_gt_u32 s84, 1
	s_cselect_b32 s86, 0xff800000, 0
	v_add_f32_e32 v68, s86, v68
	v_add_f32_e32 v69, s86, v69
	v_add_f32_e32 v70, s86, v70
	v_add_f32_e32 v71, s86, v71
	s_cmp_gt_u32 s84, 2
	s_cselect_b32 s86, 0xff800000, 0
	v_add_f32_e32 v72, s86, v72
	v_add_f32_e32 v73, s86, v73
	v_add_f32_e32 v74, s86, v74
	v_add_f32_e32 v75, s86, v75
	s_cmp_gt_u32 s84, 3
	s_cselect_b32 s86, 0xff800000, 0
	v_add_f32_e32 v76, s86, v76
	v_add_f32_e32 v77, s86, v77
	v_add_f32_e32 v78, s86, v78
	v_add_f32_e32 v79, s86, v79
	s_cmp_gt_u32 s84, 4
	s_cselect_b32 s86, 0xff800000, 0
	v_add_f32_e32 v80, s86, v80
	v_add_f32_e32 v81, s86, v81
	v_add_f32_e32 v82, s86, v82
	v_add_f32_e32 v83, s86, v83
	s_cmp_gt_u32 s84, 5
	s_cselect_b32 s86, 0xff800000, 0
	v_add_f32_e32 v84, s86, v84
	v_add_f32_e32 v85, s86, v85
	v_add_f32_e32 v86, s86, v86
	v_add_f32_e32 v87, s86, v87
	s_cmp_gt_u32 s84, 6
	s_cselect_b32 s86, 0xff800000, 0
	v_add_f32_e32 v88, s86, v88
	v_add_f32_e32 v89, s86, v89
	v_add_f32_e32 v90, s86, v90
	v_add_f32_e32 v91, s86, v91
	s_cmp_gt_u32 s84, 7
	s_cselect_b32 s86, 0xff800000, 0
	v_add_f32_e32 v92, s86, v92
	v_add_f32_e32 v93, s86, v93
	v_add_f32_e32 v94, s86, v94
	v_add_f32_e32 v95, s86, v95
	s_nop 1
; __device__ __forceinline__ void phase_attn(const Params& p, int l, LAS unsigned char* ldsb) {
;     ...
;             float inv[4];
; #pragma unroll
;             for (int j = 0; j < 4; ++j) mx[j] = fmaxf(row16_max(mx[j]), sink);
;             float sm[4] = {0.f, 0.f, 0.f, 0.f};
; #pragma unroll
;             for (int kt = 0; kt < 10; ++kt)
; #pragma unroll
;                 for (int j = 0; j < 4; ++j) { const float e = __expf(S[kt][j] - mx[j]); S[kt][j] = e; sm[j] += e; }
; #pragma unroll
;             for (int j = 0; j < 4; ++j) inv[j] = 1.f / (row16_sum(sm[j]) + __expf(sink - mx[j]));
.Lat_nomask:
	v_max3_f32 v31, v64, v65, v66
	v_max3_f32 v31, v31, v67, v68
	v_max3_f32 v31, v31, v69, v70
	v_max3_f32 v31, v31, v71, v72
	v_max3_f32 v31, v31, v73, v74
	v_max3_f32 v31, v31, v75, v76
	v_max3_f32 v31, v31, v77, v78
	v_max3_f32 v31, v31, v79, v80
	v_max3_f32 v31, v31, v81, v82
	v_max3_f32 v31, v31, v83, v84
	v_max3_f32 v31, v31, v85, v86
	v_max3_f32 v31, v31, v87, v88
	v_max3_f32 v31, v31, v89, v90
	v_max3_f32 v31, v31, v91, v92
	v_max3_f32 v31, v31, v93, v94
	v_max3_f32 v31, v31, v95, v96
	v_max3_f32 v31, v31, v97, v98
	v_max3_f32 v31, v31, v99, v100
	v_max3_f32 v31, v31, v101, v102
	v_max_f32_e32 v31, v31, v103
	ds_bpermute_b32 v33, v29, v31
	s_waitcnt lgkmcnt(0)
	v_max_f32_e32 v31, v31, v33
	ds_bpermute_b32 v33, v30, v31
	s_waitcnt lgkmcnt(0)
	v_max_f32_e32 v31, v31, v33
	v_max_f32_e32 v31, s83, v31
	v_sub_f32_e32 v64, v64, v31
	v_sub_f32_e32 v65, v65, v31
	v_sub_f32_e32 v66, v66, v31
	v_sub_f32_e32 v67, v67, v31
	v_sub_f32_e32 v68, v68, v31
	v_sub_f32_e32 v69, v69, v31
	v_sub_f32_e32 v70, v70, v31
	v_sub_f32_e32 v71, v71, v31
	v_sub_f32_e32 v72, v72, v31
	v_sub_f32_e32 v73, v73, v31
	v_sub_f32_e32 v74, v74, v31
	v_sub_f32_e32 v75, v75, v31
	v_sub_f32_e32 v76, v76, v31
	v_sub_f32_e32 v77, v77, v31
	v_sub_f32_e32 v78, v78, v31
	v_sub_f32_e32 v79, v79, v31
	v_sub_f32_e32 v80, v80, v31
	v_sub_f32_e32 v81, v81, v31
	v_sub_f32_e32 v82, v82, v31
	v_sub_f32_e32 v83, v83, v31
	v_sub_f32_e32 v84, v84, v31
	v_sub_f32_e32 v85, v85, v31
	v_sub_f32_e32 v86, v86, v31
	v_sub_f32_e32 v87, v87, v31
	v_sub_f32_e32 v88, v88, v31
	v_sub_f32_e32 v89, v89, v31
	v_sub_f32_e32 v90, v90, v31
	v_sub_f32_e32 v91, v91, v31
	v_sub_f32_e32 v92, v92, v31
	v_sub_f32_e32 v93, v93, v31
	v_sub_f32_e32 v94, v94, v31
	v_sub_f32_e32 v95, v95, v31
	v_sub_f32_e32 v96, v96, v31
	v_sub_f32_e32 v97, v97, v31
	v_sub_f32_e32 v98, v98, v31
	v_sub_f32_e32 v99, v99, v31
	v_sub_f32_e32 v100, v100, v31
	v_sub_f32_e32 v101, v101, v31
	v_sub_f32_e32 v102, v102, v31
	v_sub_f32_e32 v103, v103, v31
	v_exp_f32_e32 v64, v64
	v_exp_f32_e32 v65, v65
	v_exp_f32_e32 v66, v66
	v_exp_f32_e32 v67, v67
	v_exp_f32_e32 v68, v68
	v_exp_f32_e32 v69, v69
	v_exp_f32_e32 v70, v70
	v_exp_f32_e32 v71, v71
	v_exp_f32_e32 v72, v72
	v_exp_f32_e32 v73, v73
	v_exp_f32_e32 v74, v74
	v_exp_f32_e32 v75, v75
	v_exp_f32_e32 v76, v76
	v_exp_f32_e32 v77, v77
	v_exp_f32_e32 v78, v78
	v_exp_f32_e32 v79, v79
	v_exp_f32_e32 v80, v80
	v_exp_f32_e32 v81, v81
	v_exp_f32_e32 v82, v82
	v_exp_f32_e32 v83, v83
	v_exp_f32_e32 v84, v84
	v_exp_f32_e32 v85, v85
	v_exp_f32_e32 v86, v86
	v_exp_f32_e32 v87, v87
	v_exp_f32_e32 v88, v88
	v_exp_f32_e32 v89, v89
	v_exp_f32_e32 v90, v90
	v_exp_f32_e32 v91, v91
	v_exp_f32_e32 v92, v92
	v_exp_f32_e32 v93, v93
	v_exp_f32_e32 v94, v94
	v_exp_f32_e32 v95, v95
	v_exp_f32_e32 v96, v96
	v_exp_f32_e32 v97, v97
	v_exp_f32_e32 v98, v98
	v_exp_f32_e32 v99, v99
	v_exp_f32_e32 v100, v100
	v_exp_f32_e32 v101, v101
	v_exp_f32_e32 v102, v102
	v_exp_f32_e32 v103, v103
	v_add_f32_e32 v32, v64, v65
	v_add_f32_e32 v32, v32, v66
	v_add_f32_e32 v32, v32, v67
	v_add_f32_e32 v32, v32, v68
	v_add_f32_e32 v32, v32, v69
	v_add_f32_e32 v32, v32, v70
	v_add_f32_e32 v32, v32, v71
	v_add_f32_e32 v32, v32, v72
	v_add_f32_e32 v32, v32, v73
	v_add_f32_e32 v32, v32, v74
	v_add_f32_e32 v32, v32, v75
	v_add_f32_e32 v32, v32, v76
	v_add_f32_e32 v32, v32, v77
	v_add_f32_e32 v32, v32, v78
	v_add_f32_e32 v32, v32, v79
	v_add_f32_e32 v32, v32, v80
	v_add_f32_e32 v32, v32, v81
	v_add_f32_e32 v32, v32, v82
	v_add_f32_e32 v32, v32, v83
	v_add_f32_e32 v32, v32, v84
	v_add_f32_e32 v32, v32, v85
	v_add_f32_e32 v32, v32, v86
	v_add_f32_e32 v32, v32, v87
	v_add_f32_e32 v32, v32, v88
	v_add_f32_e32 v32, v32, v89
	v_add_f32_e32 v32, v32, v90
	v_add_f32_e32 v32, v32, v91
	v_add_f32_e32 v32, v32, v92
	v_add_f32_e32 v32, v32, v93
	v_add_f32_e32 v32, v32, v94
	v_add_f32_e32 v32, v32, v95
	v_add_f32_e32 v32, v32, v96
	v_add_f32_e32 v32, v32, v97
	v_add_f32_e32 v32, v32, v98
	v_add_f32_e32 v32, v32, v99
	v_add_f32_e32 v32, v32, v100
	v_add_f32_e32 v32, v32, v101
	v_add_f32_e32 v32, v32, v102
	v_add_f32_e32 v32, v32, v103
	ds_bpermute_b32 v33, v29, v32
	s_waitcnt lgkmcnt(0)
	v_add_f32_e32 v32, v32, v33
	ds_bpermute_b32 v33, v30, v32
	s_waitcnt lgkmcnt(0)
; #define LAS __attribute__((address_space(3)))
; __device__ __forceinline__ unsigned pk_bf16(float lo, float hi) { const f32x2_t f = {lo, hi}; return __builtin_bit_cast(unsigned, __builtin_convertvector(f, bf16x2_t)); }
; __device__ __forceinline__ void phase_attn(const Params& p, int l, LAS unsigned char* ldsb) {
;     ...
;             for (int j = 0; j < 4; ++j) inv[j] = 1.f / (row16_sum(sm[j]) + __expf(sink - mx[j]));
; #pragma unroll
;             for (int kt = 0; kt < 10; ++kt)
; #pragma unroll
;                 for (int j = 0; j < 4; ++j) Pw[(4 * fq + j) * 168 + kt * 16 + fr] = (bf16_t)(pk_bf16(S[kt][j] * inv[j], 0.f) & 0xffffu);
;             asm volatile("s_waitcnt lgkmcnt(0)" ::: "memory");
;             __builtin_amdgcn_wave_barrier();
;             f32x4 O[4];
; #pragma unroll
;             for (int dt = 0; dt < 4; ++dt) O[dt] = (f32x4){0.f, 0.f, 0.f, 0.f};
; #pragma unroll
;             for (int kk = 0; kk < 5; ++kk) {
;                 const bf16x8 pa = *(LAS const bf16x8*)(Pw + fr * 168 + kk * 32 + fq * 8);
; #pragma unroll
;                 for (int dt = 0; dt < 4; ++dt) {
;                     const bf16x8 vb = *(LAS const bf16x8*)(Vt + (dt * 16 + fr) * 264 + kstart + kk * 32 + fq * 8);
;                     O[dt] = __builtin_amdgcn_mfma_f32_16x16x32_bf16(pa, vb, O[dt], 0, 0, 0);
;                 }
;             }
; #pragma unroll
;             for (int dt = 0; dt < 4; ++dt)
; #pragma unroll
;                 for (int j = 0; j < 4; ++j) ATT[(size_t)(tokc + q0 + 4 * fq + j) * 512 + hq * 64 + dt * 16 + fr] = (bf16_t)(pk_bf16(O[dt][j], 0.f) & 0xffffu);
;             asm volatile("s_waitcnt lgkmcnt(0)" ::: "memory");
;             __builtin_amdgcn_wave_barrier();
;         }
	v_add_f32_e32 v32, v32, v33
	v_sub_f32_e32 v33, s83, v31
	v_exp_f32_e32 v33, v33
	s_nop 0
	v_add_f32_e32 v32, v32, v33
	v_rcp_f32_e32 v36, v32
	s_nop 0
	v_fma_f32 v33, -v32, v36, 2.0
	v_mul_f32_e32 v36, v36, v33
	v_mul_f32_e32 v64, v36, v64
	v_mul_f32_e32 v65, v36, v65
	v_cvt_pk_bf16_f32 v144, v64, v65
	v_mul_f32_e32 v66, v36, v66
	v_mul_f32_e32 v67, v36, v67
	v_cvt_pk_bf16_f32 v145, v66, v67
	v_mul_f32_e32 v68, v36, v68
	v_mul_f32_e32 v69, v36, v69
	v_cvt_pk_bf16_f32 v146, v68, v69
	v_mul_f32_e32 v70, v36, v70
	v_mul_f32_e32 v71, v36, v71
	v_cvt_pk_bf16_f32 v147, v70, v71
	v_mul_f32_e32 v72, v36, v72
	v_mul_f32_e32 v73, v36, v73
	v_cvt_pk_bf16_f32 v148, v72, v73
	v_mul_f32_e32 v74, v36, v74
	v_mul_f32_e32 v75, v36, v75
	v_cvt_pk_bf16_f32 v149, v74, v75
	v_mul_f32_e32 v76, v36, v76
	v_mul_f32_e32 v77, v36, v77
	v_cvt_pk_bf16_f32 v150, v76, v77
	v_mul_f32_e32 v78, v36, v78
	v_mul_f32_e32 v79, v36, v79
	v_cvt_pk_bf16_f32 v151, v78, v79
	v_mul_f32_e32 v80, v36, v80
	v_mul_f32_e32 v81, v36, v81
	v_cvt_pk_bf16_f32 v152, v80, v81
	v_mul_f32_e32 v82, v36, v82
	v_mul_f32_e32 v83, v36, v83
	v_cvt_pk_bf16_f32 v153, v82, v83
	v_mul_f32_e32 v84, v36, v84
	v_mul_f32_e32 v85, v36, v85
	v_cvt_pk_bf16_f32 v154, v84, v85
	v_mul_f32_e32 v86, v36, v86
	v_mul_f32_e32 v87, v36, v87
	v_cvt_pk_bf16_f32 v155, v86, v87
	v_mul_f32_e32 v88, v36, v88
	v_mul_f32_e32 v89, v36, v89
	v_cvt_pk_bf16_f32 v156, v88, v89
	v_mul_f32_e32 v90, v36, v90
	v_mul_f32_e32 v91, v36, v91
	v_cvt_pk_bf16_f32 v157, v90, v91
	v_mul_f32_e32 v92, v36, v92
	v_mul_f32_e32 v93, v36, v93
	v_cvt_pk_bf16_f32 v158, v92, v93
	v_mul_f32_e32 v94, v36, v94
	v_mul_f32_e32 v95, v36, v95
	v_cvt_pk_bf16_f32 v159, v94, v95
	v_mul_f32_e32 v96, v36, v96
	v_mul_f32_e32 v97, v36, v97
	v_cvt_pk_bf16_f32 v160, v96, v97
	v_mul_f32_e32 v98, v36, v98
	v_mul_f32_e32 v99, v36, v99
	v_cvt_pk_bf16_f32 v161, v98, v99
	v_mul_f32_e32 v100, v36, v100
	v_mul_f32_e32 v101, v36, v101
	v_cvt_pk_bf16_f32 v162, v100, v101
	v_mul_f32_e32 v102, v36, v102
	v_mul_f32_e32 v103, v36, v103
	v_cvt_pk_bf16_f32 v163, v102, v103
	s_sleep 64
	ds_read_b64_tr_b16 v[200:201], v23 offset:0
	ds_read_b64_tr_b16 v[202:203], v23 offset:2048
	ds_read_b64_tr_b16 v[204:205], v24 offset:0
	ds_read_b64_tr_b16 v[206:207], v24 offset:2048
	ds_read_b64_tr_b16 v[208:209], v25 offset:0
	ds_read_b64_tr_b16 v[210:211], v25 offset:2048
	ds_read_b64_tr_b16 v[220:221], v26 offset:0
	ds_read_b64_tr_b16 v[222:223], v26 offset:2048
	ds_read_b64_tr_b16 v[224:225], v23 offset:4096
	ds_read_b64_tr_b16 v[226:227], v23 offset:6144
	ds_read_b64_tr_b16 v[228:229], v24 offset:4096
	ds_read_b64_tr_b16 v[230:231], v24 offset:6144
	ds_read_b64_tr_b16 v[232:233], v25 offset:4096
	ds_read_b64_tr_b16 v[234:235], v25 offset:6144
	ds_read_b64_tr_b16 v[236:237], v26 offset:4096
	ds_read_b64_tr_b16 v[238:239], v26 offset:6144
	s_waitcnt lgkmcnt(14)
	v_mfma_f32_16x16x32_bf16 v[164:167], v[200:203], v[144:147], 0
	s_waitcnt lgkmcnt(12)
	v_mfma_f32_16x16x32_bf16 v[168:171], v[204:207], v[144:147], 0
	s_waitcnt lgkmcnt(10)
	v_mfma_f32_16x16x32_bf16 v[172:175], v[208:211], v[144:147], 0
	s_waitcnt lgkmcnt(8)
	v_mfma_f32_16x16x32_bf16 v[196:199], v[220:223], v[144:147], 0
	ds_read_b64_tr_b16 v[200:201], v23 offset:8192
	ds_read_b64_tr_b16 v[202:203], v23 offset:10240
	ds_read_b64_tr_b16 v[204:205], v24 offset:8192
	ds_read_b64_tr_b16 v[206:207], v24 offset:10240
	ds_read_b64_tr_b16 v[208:209], v25 offset:8192
	ds_read_b64_tr_b16 v[210:211], v25 offset:10240
	ds_read_b64_tr_b16 v[220:221], v26 offset:8192
	ds_read_b64_tr_b16 v[222:223], v26 offset:10240
	s_waitcnt lgkmcnt(14)
	v_mfma_f32_16x16x32_bf16 v[164:167], v[224:227], v[148:151], v[164:167]
	s_waitcnt lgkmcnt(12)
	v_mfma_f32_16x16x32_bf16 v[168:171], v[228:231], v[148:151], v[168:171]
	s_waitcnt lgkmcnt(10)
	v_mfma_f32_16x16x32_bf16 v[172:175], v[232:235], v[148:151], v[172:175]
	s_waitcnt lgkmcnt(8)
	v_mfma_f32_16x16x32_bf16 v[196:199], v[236:239], v[148:151], v[196:199]
	ds_read_b64_tr_b16 v[224:225], v23 offset:12288
	ds_read_b64_tr_b16 v[226:227], v23 offset:14336
	ds_read_b64_tr_b16 v[228:229], v24 offset:12288
	ds_read_b64_tr_b16 v[230:231], v24 offset:14336
	ds_read_b64_tr_b16 v[232:233], v25 offset:12288
	ds_read_b64_tr_b16 v[234:235], v25 offset:14336
	ds_read_b64_tr_b16 v[236:237], v26 offset:12288
	ds_read_b64_tr_b16 v[238:239], v26 offset:14336
	s_waitcnt lgkmcnt(14)
	v_mfma_f32_16x16x32_bf16 v[164:167], v[200:203], v[152:155], v[164:167]
	s_waitcnt lgkmcnt(12)
	v_mfma_f32_16x16x32_bf16 v[168:171], v[204:207], v[152:155], v[168:171]
	s_waitcnt lgkmcnt(10)
	v_mfma_f32_16x16x32_bf16 v[172:175], v[208:211], v[152:155], v[172:175]
	s_waitcnt lgkmcnt(8)
	v_mfma_f32_16x16x32_bf16 v[196:199], v[220:223], v[152:155], v[196:199]
	ds_read_b64_tr_b16 v[200:201], v23 offset:16384
	ds_read_b64_tr_b16 v[202:203], v23 offset:18432
	ds_read_b64_tr_b16 v[204:205], v24 offset:16384
	ds_read_b64_tr_b16 v[206:207], v24 offset:18432
	ds_read_b64_tr_b16 v[208:209], v25 offset:16384
	ds_read_b64_tr_b16 v[210:211], v25 offset:18432
	ds_read_b64_tr_b16 v[220:221], v26 offset:16384
	ds_read_b64_tr_b16 v[222:223], v26 offset:18432
	s_waitcnt lgkmcnt(14)
	v_mfma_f32_16x16x32_bf16 v[164:167], v[224:227], v[156:159], v[164:167]
	s_waitcnt lgkmcnt(12)
	v_mfma_f32_16x16x32_bf16 v[168:171], v[228:231], v[156:159], v[168:171]
	s_waitcnt lgkmcnt(10)
	v_mfma_f32_16x16x32_bf16 v[172:175], v[232:235], v[156:159], v[172:175]
	s_waitcnt lgkmcnt(8)
	v_mfma_f32_16x16x32_bf16 v[196:199], v[236:239], v[156:159], v[196:199]
	s_waitcnt lgkmcnt(6)
	v_mfma_f32_16x16x32_bf16 v[164:167], v[200:203], v[160:163], v[164:167]
	s_waitcnt lgkmcnt(4)
	v_mfma_f32_16x16x32_bf16 v[168:171], v[204:207], v[160:163], v[168:171]
	s_waitcnt lgkmcnt(2)
	v_mfma_f32_16x16x32_bf16 v[172:175], v[208:211], v[160:163], v[172:175]
	s_waitcnt lgkmcnt(0)
	v_mfma_f32_16x16x32_bf16 v[196:199], v[220:223], v[160:163], v[196:199]
	s_nop 1
	v_cvt_pk_bf16_f32 v38, v164, v165
	v_cvt_pk_bf16_f32 v39, v166, v167
	global_store_dwordx2 v28, v[38:39], s[42:43] offset:0
	v_cvt_pk_bf16_f32 v38, v168, v169
	v_cvt_pk_bf16_f32 v39, v170, v171
	global_store_dwordx2 v28, v[38:39], s[42:43] offset:32
	v_cvt_pk_bf16_f32 v38, v172, v173
	v_cvt_pk_bf16_f32 v39, v174, v175
	global_store_dwordx2 v28, v[38:39], s[42:43] offset:64
	v_cvt_pk_bf16_f32 v38, v196, v197
	v_cvt_pk_bf16_f32 v39, v198, v199
	global_store_dwordx2 v28, v[38:39], s[42:43] offset:96
	s_waitcnt vmcnt(4)
	s_add_u32 s48, s48, 1
	s_cmp_lt_u32 s48, 8
	s_cbranch_scc1 .Lat_rt
	s_add_u32 s87, s87, 1
	s_cmp_lt_u32 s87, 2
	s_cbranch_scc0 .Lat_end
	s_xor_b32 s32, s32, 16384
	s_waitcnt lgkmcnt(0)
	s_barrier
	s_branch .Lat_again
